# GEMM2 phase: second workgroup of each CU starts ~5.5us later so its HBM-bound epilogue alternates with the sibling's k-loop
# baseline (speedup 1.0000x reference)
; #define VB_LOAD() __builtin_amdgcn_readfirstlane((int)bst[8])
; __global__ void __launch_bounds__(256, 2) mega(Params P) {
;     ...
;     xcd_barrier(xb);
;     for (int tile = VB_LOAD(); tile < 128 * 8; tile += G) gemm_tile<2>(P, tile >> 3, tile & 7, smem);
.LBB0_1151:
	s_or_b64 exec, exec, s[18:19]
	s_add_i32 s0, 0, 0x10030
	v_mov_b32_e32 v2, s0
	s_barrier
	ds_read_b32 v2, v2
	s_waitcnt lgkmcnt(0)
	v_readfirstlane_b32 s6, v2
	s_getreg_b32 s0, hwreg(HW_REG_LDS_ALLOC, 0, 8)
	s_cmp_eq_u32 s0, 0
	s_cbranch_scc1 .Lp3stag_skip
	s_sleep 127
	s_sleep 60
.Lp3stag_skip:
	s_cmpk_gt_i32 s6, 0x3ff
	s_cbranch_scc1 .LBB0_1162
	s_add_u32 s0, s28, 0x2050000
	s_addc_u32 s1, s29, 0
	s_add_u32 s2, s28, 0x94c5000
	s_addc_u32 s3, s29, 0
	s_add_u32 s7, s28, 0x92b3000
	s_addc_u32 s8, s29, 0
	s_lshl_b32 s9, s6, 4
	s_lshl_b32 s10, s33, 4
	s_movk_i32 s11, 0x810
	s_movk_i32 s12, 0x1c00
	s_movk_i32 s13, 0x70
	v_mov_b32_e32 v99, 0
	s_movk_i32 s14, 0x110
	s_branch .LBB0_1154
